# HGRN2 gates: exp2 argument formed as min(x*-log2e, 40*log2e) instead of canonicalise/min/mul (bit-identical, 16 fewer VALU per tile)
# baseline (speedup 1.0000x reference)
; __device__ __forceinline__ void scan_hgrn_mfma(const Params& P, unsigned char* LB, int l, int c) {
;     ...
;         { f32x2 fc[4];
; #pragma unroll
;           for (int r = 0; r < 4; ++r) {
;               const float eq0 = 1.f + __expf(fminf(-pq[r].x, 40.f)), ef0 = 1.f + __expf(fminf(-pf[r].x, 40.f)), r0_ = __builtin_amdgcn_rcpf(eq0 * ef0);
;               const float eq1 = 1.f + __expf(fminf(-pq[r].y, 40.f)), ef1 = 1.f + __expf(fminf(-pf[r].y, 40.f)), r1_ = __builtin_amdgcn_rcpf(eq1 * ef1);
;               q[r].x = pq[r].x * (ef0 * r0_) * 0.08838834764831845f; q[r].y = pq[r].y * (ef1 * r1_) * 0.08838834764831845f;
;               const float f0 = lb2.x + (1.f - lb2.x) * (eq0 * r0_), f1 = lb2.y + (1.f - lb2.y) * (eq1 * r1_);
;               kk[r].x = 1.f - f0; kk[r].y = 1.f - f1; fc[r].x = fmaxf(f0, 1e-4f); fc[r].y = fmaxf(f1, 1e-4f); vv[r] = pv[r];
;           }
;           pre[0] = fc[0]; pre[1] = pre[0] * fc[1]; pre[2] = pre[1] * fc[2]; pre[3] = pre[2] * fc[3];
;           suf[3] = (f32x2){1.f, 1.f}; suf[2] = fc[3]; suf[1] = suf[2] * fc[2]; suf[0] = suf[1] * fc[1]; }
.LBB0_162:
	v_mul_f32_e32 v37, 0xbfb8aa3b, v66
	v_min_f32_e32 v37, 0x4266d4ca, v37
	v_exp_f32_e32 v38, v37
	v_mul_f32_e32 v36, 0xbfb8aa3b, v70
	v_mul_f32_e32 v37, 0xbfb8aa3b, v71
	v_mul_f32_e32 v39, 0xbfb8aa3b, v67
	v_min_f32_e32 v36, 0x4266d4ca, v36
	v_min_f32_e32 v37, 0x4266d4ca, v37
	v_min_f32_e32 v39, 0x4266d4ca, v39
	v_exp_f32_e32 v36, v36
	v_exp_f32_e32 v39, v39
	v_exp_f32_e32 v37, v37
	v_mul_f32_e32 v41, 0xbfb8aa3b, v65
	v_pk_add_f32 v[94:95], v[38:39], 1.0 op_sel_hi:[1,0]
	v_pk_add_f32 v[36:37], v[36:37], 1.0 op_sel_hi:[1,0]
	v_min_f32_e32 v41, 0x4266d4ca, v41
	v_pk_mul_f32 v[38:39], v[36:37], v[94:95]
	v_exp_f32_e32 v41, v41
	v_rcp_f32_e32 v99, v39
	v_mul_f32_e32 v39, 0xbfb8aa3b, v64
	v_min_f32_e32 v39, 0x4266d4ca, v39
	v_rcp_f32_e32 v98, v38
	v_exp_f32_e32 v40, v39
	v_mul_f32_e32 v38, 0xbfb8aa3b, v68
	v_mul_f32_e32 v39, 0xbfb8aa3b, v69
	v_min_f32_e32 v38, 0x4266d4ca, v38
	v_min_f32_e32 v39, 0x4266d4ca, v39
	v_exp_f32_e32 v38, v38
	v_exp_f32_e32 v39, v39
	v_pk_add_f32 v[86:87], v[40:41], 1.0 op_sel_hi:[1,0]
	v_pk_mul_f32 v[36:37], v[36:37], v[98:99]
	s_add_i32 s22, s38, s43
	v_pk_add_f32 v[38:39], v[38:39], 1.0 op_sel_hi:[1,0]
	v_pk_fma_f32 v[102:103], v[54:55], v[36:37], v[0:1]
	v_pk_mul_f32 v[40:41], v[38:39], v[86:87]
	s_add_i32 s20, s22, 32
	v_rcp_f32_e32 v88, v40
	v_rcp_f32_e32 v89, v41
	v_mul_f32_e32 v41, 0xbfb8aa3b, v63
	v_min_f32_e32 v41, 0x4266d4ca, v41
	v_pk_mul_f32 v[36:37], v[38:39], v[88:89]
	v_mul_f32_e32 v39, 0xbfb8aa3b, v62
	v_min_f32_e32 v39, 0x4266d4ca, v39
	v_exp_f32_e32 v40, v39
	v_mul_f32_e32 v38, 0xbfb8aa3b, v50
	v_mul_f32_e32 v39, 0xbfb8aa3b, v51
	v_min_f32_e32 v38, 0x4266d4ca, v38
	v_min_f32_e32 v39, 0x4266d4ca, v39
	v_exp_f32_e32 v38, v38
	v_exp_f32_e32 v41, v41
	v_exp_f32_e32 v39, v39
	v_pk_fma_f32 v[92:93], v[54:55], v[36:37], v[0:1]
	s_add_i32 s21, s22, 0xffffff20
	v_pk_add_f32 v[80:81], v[40:41], 1.0 op_sel_hi:[1,0]
	v_pk_add_f32 v[36:37], v[38:39], 1.0 op_sel_hi:[1,0]
	v_pk_mul_f32 v[38:39], v[36:37], v[80:81]
	v_mul_f32_e32 v41, 0xbfb8aa3b, v59
	v_rcp_f32_e32 v85, v39
	v_mul_f32_e32 v39, 0xbfb8aa3b, v58
	v_min_f32_e32 v39, 0x4266d4ca, v39
	v_rcp_f32_e32 v84, v38
	v_exp_f32_e32 v40, v39
	v_mul_f32_e32 v38, 0xbfb8aa3b, v48
	v_mul_f32_e32 v39, 0xbfb8aa3b, v49
	s_cmpk_lt_i32 s20, 0x100
	v_min_f32_e32 v38, 0x4266d4ca, v38
	v_min_f32_e32 v39, 0x4266d4ca, v39
	v_min_f32_e32 v41, 0x4266d4ca, v41
	s_cselect_b32 s23, 0xff, s33
	v_exp_f32_e32 v38, v38
	v_exp_f32_e32 v41, v41
	v_exp_f32_e32 v39, v39
	s_cselect_b32 s24, s20, s21
	s_cselect_b32 s25, s39, s36
	s_add_i32 s20, s41, s23
	s_add_i32 s20, s20, s40
	s_sub_i32 s23, s20, 32
	s_and_b64 s[20:21], s[6:7], exec
	v_pk_add_f32 v[72:73], v[40:41], 1.0 op_sel_hi:[1,0]
	v_pk_add_f32 v[38:39], v[38:39], 1.0 op_sel_hi:[1,0]
	s_cselect_b32 s20, s24, s23
	v_pk_mul_f32 v[40:41], v[38:39], v[72:73]
	s_add_i32 s23, s20, s25
	v_rcp_f32_e32 v74, v40
	v_rcp_f32_e32 v75, v41
	s_mul_i32 s21, s23, 0x2a00
	s_mul_hi_i32 s20, s23, 0x2a00
	s_add_u32 s21, s94, s21
	s_addc_u32 s24, s95, s20
	s_add_u32 s20, s21, s42
	v_pk_mul_f32 v[38:39], v[38:39], v[74:75]
	s_addc_u32 s21, s24, 0
	s_mov_b64 s[50:51], s[20:21]
	v_pk_fma_f32 v[78:79], v[54:55], v[38:39], v[0:1]
	v_lshl_add_u64 v[38:39], s[20:21], 0, v[2:3]
	v_mad_i64_i32 v[40:41], s[20:21], s23, v191, v[60:61]
	s_add_u32 s50, s50, s47
	s_addc_u32 s51, s51, s48
	s_add_i32 s24, s23, s46
	v_lshl_add_u64 v[42:43], s[50:51], 0, v[2:3]
	v_mad_i64_i32 v[58:59], s[20:21], s24, v191, v[60:61]
	v_pk_mul_f32 v[36:37], v[36:37], v[84:85]
	v_max_f32_e32 v106, 0x38d1b717, v102
	v_max_f32_e32 v107, 0x38d1b717, v103
	v_max_f32_e32 v110, 0x38d1b717, v92
	v_max_f32_e32 v111, 0x38d1b717, v93
	v_pk_fma_f32 v[90:91], v[54:55], v[36:37], v[0:1]
	s_mov_b32 s2, 0x26201000
	v_max_f32_e32 v36, 0x38d1b717, v90
	v_max_f32_e32 v37, 0x38d1b717, v91
	v_pk_mul_f32 v[108:109], v[110:111], v[106:107]
	v_add_co_u32_e32 v38, vcc, s2, v38
	v_max_f32_e32 v100, 0x38d1b717, v78
	v_max_f32_e32 v101, 0x38d1b717, v79
	v_pk_mul_f32 v[96:97], v[36:37], v[108:109]
	v_addc_co_u32_e32 v39, vcc, 0, v39, vcc
	v_pk_mul_f32 v[82:83], v[100:101], v[96:97]
	v_add_co_u32_e32 v42, vcc, s2, v42
	s_add_u32 s50, s50, s47
	s_addc_u32 s51, s51, s48
	s_add_i32 s25, s24, s46
	s_mov_b64 s[20:21], s[50:51]
	ds_write_b64 v125, v[82:83] offset:58368
	s_waitcnt lgkmcnt(0)
	s_barrier
	v_addc_co_u32_e32 v43, vcc, 0, v43, vcc
	global_load_dword v128, v[38:39], off offset:2048
	global_load_dwordx2 v[66:67], v[40:41], off offset:64
	global_load_dword v129, v[42:43], off offset:2048
	global_load_dwordx2 v[64:65], v[58:59], off offset:64
	v_lshl_add_u64 v[38:39], s[20:21], 0, v[2:3]
	v_mad_i64_i32 v[40:41], s[20:21], s25, v191, v[60:61]
	v_add_co_u32_e32 v38, vcc, s2, v38
	s_nop 1
	v_addc_co_u32_e32 v39, vcc, 0, v39, vcc
	s_add_u32 s50, s50, s47
	s_addc_u32 s51, s51, s48
	s_add_i32 s22, s25, s46
	v_lshl_add_u64 v[42:43], s[50:51], 0, v[2:3]
	v_add_co_u32_e32 v42, vcc, s2, v42
	v_mad_i64_i32 v[58:59], s[20:21], s22, v191, v[60:61]
	s_nop 0
	v_addc_co_u32_e32 v43, vcc, 0, v43, vcc
	global_load_dword v131, v[38:39], off offset:2048
	global_load_dwordx2 v[62:63], v[40:41], off offset:64
	global_load_dword v132, v[42:43], off offset:2048
	s_nop 0
	global_load_dwordx2 v[58:59], v[58:59], off offset:64
	v_mad_i64_i32 v[38:39], s[20:21], s23, v190, v[56:57]
	v_mad_i64_i32 v[40:41], s[20:21], s24, v190, v[56:57]
	v_mad_i64_i32 v[42:43], s[20:21], s25, v190, v[56:57]
	v_mad_i64_i32 v[104:105], s[20:21], s22, v190, v[56:57]
	global_load_ushort v136, v[38:39], off
	global_load_ushort v137, v[40:41], off
	global_load_ushort v130, v[42:43], off
	global_load_ushort v135, v[104:105], off
	v_pk_mul_f32 v[112:113], v[100:101], v[36:37]
	ds_read2st64_b64 v[40:43], v124 offset0:114 offset1:115
	ds_read2st64_b64 v[36:39], v124 offset0:116 offset1:117
	s_mov_b64 s[20:21], -1
	s_and_b64 vcc, exec, s[26:27]
	s_cbranch_vccz .LBB0_164
	v_pk_mul_f32 v[104:105], v[110:111], v[112:113]
	s_mov_b64 s[20:21], 0
	s_waitcnt lgkmcnt(1)
	v_pk_mul_f32 v[110:111], v[104:105], v[42:43]
	s_nop 0
	v_cndmask_b32_e64 v105, v105, v111, s[18:19]
	v_cndmask_b32_e64 v104, v104, v110, s[18:19]
	v_rcp_f32_e32 v114, v104
	v_rcp_f32_e32 v115, v105
